# v28: attention loop: V prefetch reads interleaved into the K.Q gaps (tail shortened), K addresses for the next tile computed in the gaps
# baseline (speedup 1.0000x reference)
.Lat_noqk1_2:
	s_mov_b32 s5, 1
	s_mov_b32 s12, 16384
	v_add_u32_e32 v188, s12, v157
	v_add_u32_e32 v189, s12, v158
	v_add_u32_e32 v222, s12, v159
	v_add_u32_e32 v223, s12, v160
	s_mov_b32 s84, 32768
	v_add_u32_e32 v215, s84, v161
	v_add_u32_e32 v165, s84, v162
	v_add_u32_e32 v216, s84, v163
	v_add_u32_e32 v217, s84, v164
	ds_read_b64_tr_b16 v[224:225], v215 offset:0
	ds_read_b64_tr_b16 v[226:227], v215 offset:2048
	ds_read_b64_tr_b16 v[228:229], v165 offset:0
	ds_read_b64_tr_b16 v[230:231], v165 offset:2048
	ds_read_b64_tr_b16 v[232:233], v216 offset:0
	ds_read_b64_tr_b16 v[234:235], v216 offset:2048
	ds_read_b64_tr_b16 v[236:237], v217 offset:0
	ds_read_b64_tr_b16 v[238:239], v217 offset:2048
	ds_read_b64_tr_b16 v[240:241], v215 offset:4096
	ds_read_b64_tr_b16 v[242:243], v215 offset:6144
	ds_read_b64_tr_b16 v[130:131], v165 offset:4096
	ds_read_b64_tr_b16 v[132:133], v165 offset:6144
	ds_read_b64_tr_b16 v[134:135], v216 offset:4096
	ds_read_b64_tr_b16 v[136:137], v216 offset:6144
	ds_read_b64_tr_b16 v[184:185], v217 offset:4096
	ds_read_b64_tr_b16 v[186:187], v217 offset:6144
	s_waitcnt vmcnt(3) lgkmcnt(15)
	s_barrier
.Lat_loop:
	s_cmp_ge_i32 s5, s81
	s_cbranch_scc1 .Lat_rare_8
	s_waitcnt lgkmcnt(2)
	v_mfma_f32_32x32x16_bf16 v[0:15], v[224:227], v[114:117], v[0:15]
	v_exp_f32_e32 v82, v82
	v_exp_f32_e32 v83, v83
	ds_read_b64_tr_b16 v[224:225], v215 offset:8192
	ds_read_b64_tr_b16 v[226:227], v215 offset:10240
	v_mfma_f32_32x32x16_bf16 v[16:31], v[228:231], v[114:117], v[16:31]
	v_exp_f32_e32 v84, v84
	v_exp_f32_e32 v85, v85
	v_add_f32_e32 v180, v82, v83
	ds_read_b64_tr_b16 v[228:229], v165 offset:8192
	ds_read_b64_tr_b16 v[230:231], v165 offset:10240
	v_mfma_f32_32x32x16_bf16 v[32:47], v[232:235], v[114:117], v[32:47]
	v_exp_f32_e32 v86, v86
	v_exp_f32_e32 v87, v87
	v_add_f32_e32 v180, v180, v84
	v_add_f32_e32 v180, v180, v85
	ds_read_b64_tr_b16 v[232:233], v216 offset:8192
	ds_read_b64_tr_b16 v[234:235], v216 offset:10240
	v_mfma_f32_32x32x16_bf16 v[48:63], v[236:239], v[114:117], v[48:63]
	v_exp_f32_e32 v88, v88
	v_exp_f32_e32 v89, v89
	v_add_f32_e32 v180, v180, v86
	v_add_f32_e32 v180, v180, v87
	ds_read_b64_tr_b16 v[236:237], v217 offset:8192
	ds_read_b64_tr_b16 v[238:239], v217 offset:10240
	s_waitcnt lgkmcnt(8)
	v_mfma_f32_32x32x16_bf16 v[0:15], v[240:243], v[118:121], v[0:15]
	v_exp_f32_e32 v90, v90
	v_exp_f32_e32 v91, v91
	v_add_f32_e32 v180, v180, v88
	v_cvt_pk_bf16_f32 v114, v82, v83
	ds_read_b64_tr_b16 v[240:241], v215 offset:12288
	ds_read_b64_tr_b16 v[242:243], v215 offset:14336
	v_mfma_f32_32x32x16_bf16 v[16:31], v[130:133], v[118:121], v[16:31]
	v_exp_f32_e32 v92, v92
	v_exp_f32_e32 v93, v93
	v_add_f32_e32 v180, v180, v89
	v_cvt_pk_bf16_f32 v115, v84, v85
	ds_read_b64_tr_b16 v[130:131], v165 offset:12288
	ds_read_b64_tr_b16 v[132:133], v165 offset:14336
	v_mfma_f32_32x32x16_bf16 v[32:47], v[134:137], v[118:121], v[32:47]
	v_exp_f32_e32 v94, v94
	v_exp_f32_e32 v95, v95
	v_add_f32_e32 v180, v180, v90
	v_cvt_pk_bf16_f32 v116, v86, v87
	ds_read_b64_tr_b16 v[134:135], v216 offset:12288
	ds_read_b64_tr_b16 v[136:137], v216 offset:14336
	v_mfma_f32_32x32x16_bf16 v[48:63], v[184:187], v[118:121], v[48:63]
	v_exp_f32_e32 v96, v96
	v_exp_f32_e32 v97, v97
	v_add_f32_e32 v180, v180, v91
	v_cvt_pk_bf16_f32 v117, v88, v89
	ds_read_b64_tr_b16 v[184:185], v217 offset:12288
	ds_read_b64_tr_b16 v[186:187], v217 offset:14336
	s_waitcnt lgkmcnt(8)
	v_mfma_f32_32x32x16_bf16 v[0:15], v[224:227], v[122:125], v[0:15]
	v_exp_f32_e32 v98, v98
	v_exp_f32_e32 v99, v99
	v_add_f32_e32 v180, v180, v92
	v_cvt_pk_bf16_f32 v118, v90, v91
	v_mfma_f32_32x32x16_bf16 v[16:31], v[228:231], v[122:125], v[16:31]
	v_exp_f32_e32 v100, v100
	v_exp_f32_e32 v101, v101
	v_add_f32_e32 v180, v180, v93
	v_cvt_pk_bf16_f32 v119, v92, v93
	v_mfma_f32_32x32x16_bf16 v[32:47], v[232:235], v[122:125], v[32:47]
	v_exp_f32_e32 v102, v102
	v_exp_f32_e32 v103, v103
	v_add_f32_e32 v180, v180, v94
	v_cvt_pk_bf16_f32 v120, v94, v95
	v_mfma_f32_32x32x16_bf16 v[48:63], v[236:239], v[122:125], v[48:63]
	v_exp_f32_e32 v104, v104
	v_exp_f32_e32 v105, v105
	v_add_f32_e32 v180, v180, v95
	v_cvt_pk_bf16_f32 v121, v96, v97
	ds_read_b128 v[224:227], v188
	ds_read_b128 v[228:231], v189
	ds_read_b128 v[232:235], v222
	ds_read_b128 v[236:239], v223
	s_waitcnt lgkmcnt(4)
	v_mfma_f32_32x32x16_bf16 v[0:15], v[240:243], v[126:129], v[0:15]
	v_exp_f32_e32 v106, v106
	v_exp_f32_e32 v107, v107
	v_add_f32_e32 v180, v180, v96
	v_add_f32_e32 v180, v180, v97
	v_mfma_f32_32x32x16_bf16 v[16:31], v[130:133], v[126:129], v[16:31]
	v_exp_f32_e32 v108, v108
	v_exp_f32_e32 v109, v109
	v_add_f32_e32 v180, v180, v98
	v_add_f32_e32 v180, v180, v99
	v_mfma_f32_32x32x16_bf16 v[32:47], v[134:137], v[126:129], v[32:47]
	v_exp_f32_e32 v110, v110
	v_exp_f32_e32 v111, v111
	v_add_f32_e32 v180, v180, v100
	v_add_f32_e32 v180, v180, v101
	v_mfma_f32_32x32x16_bf16 v[48:63], v[184:187], v[126:129], v[48:63]
	v_exp_f32_e32 v112, v112
	v_exp_f32_e32 v113, v113
	v_add_f32_e32 v180, v180, v102
	v_add_f32_e32 v180, v180, v103
	ds_read_b128 v[240:243], v188 offset:4096
	ds_read_b128 v[130:133], v189 offset:4096
	ds_read_b128 v[134:137], v222 offset:4096
	ds_read_b128 v[184:187], v223 offset:4096
	s_waitcnt lgkmcnt(4)
	v_mfma_f32_32x32x16_bf16 v[82:97], v[224:227], v[150:153], v[64:79]
	v_add_f32_e32 v180, v180, v104
	v_add_f32_e32 v180, v180, v105
	v_add_f32_e32 v180, v180, v106
	v_cvt_pk_bf16_f32 v122, v98, v99
	v_cvt_pk_bf16_f32 v123, v100, v101
	s_add_i32 m0, s13, s68
	s_nop 0
	global_load_lds_dwordx4 v154, s[14:15]
	v_mfma_f32_32x32x16_bf16 v[82:97], v[228:231], v[146:149], v[82:97]
	v_add_f32_e32 v180, v180, v107
	v_add_f32_e32 v180, v180, v108
	v_add_f32_e32 v180, v180, v109
	v_cvt_pk_bf16_f32 v124, v102, v103
	v_cvt_pk_bf16_f32 v125, v104, v105
	s_add_i32 m0, s17, s69
	s_nop 0
	global_load_lds_dwordx4 v155, s[18:19]
	v_mfma_f32_32x32x16_bf16 v[82:97], v[232:235], v[142:145], v[82:97]
	v_add_f32_e32 v180, v180, v110
	v_add_f32_e32 v180, v180, v111
	v_cvt_pk_bf16_f32 v126, v106, v107
	v_cvt_pk_bf16_f32 v127, v108, v109
	s_add_i32 m0, m0, 0x400
	s_nop 0
	global_load_lds_dwordx4 v156, s[18:19]
	v_mfma_f32_32x32x16_bf16 v[82:97], v[236:239], v[138:141], v[82:97]
	v_add_f32_e32 v180, v180, v112
	v_add_f32_e32 v180, v180, v113
	v_cvt_pk_bf16_f32 v128, v110, v111
	v_cvt_pk_bf16_f32 v129, v112, v113
	v_cmp_ngt_f32_e32 vcc, s23, v180
	s_add_i32 s12, s12, 8192
	s_cmp_eq_u32 s12, 32768
	s_cselect_b32 s12, 0, s12
	s_add_i32 s84, s84, 16384
	s_cmp_eq_u32 s84, 114688
	s_cselect_b32 s84, 32768, s84
	s_waitcnt lgkmcnt(0)
	v_mfma_f32_32x32x16_bf16 v[98:113], v[240:243], v[150:153], v[64:79]
	v_add_u32_e32 v215, s84, v161
	v_add_u32_e32 v165, s84, v162
	v_add_u32_e32 v216, s84, v163
	v_add_u32_e32 v217, s84, v164
	ds_read_b64_tr_b16 v[224:225], v215 offset:0
	ds_read_b64_tr_b16 v[226:227], v215 offset:2048
	ds_read_b64_tr_b16 v[240:241], v215 offset:4096
	ds_read_b64_tr_b16 v[242:243], v215 offset:6144
	s_add_i32 s13, s13, 8192
	s_cmp_eq_u32 s13, 32768
	s_cselect_b32 s13, 0, s13
	v_add_u32_e32 v188, s12, v157
	v_add_u32_e32 v189, s12, v158
	v_mfma_f32_32x32x16_bf16 v[98:113], v[130:133], v[146:149], v[98:113]
	ds_read_b64_tr_b16 v[228:229], v165 offset:0
	ds_read_b64_tr_b16 v[230:231], v165 offset:2048
	ds_read_b64_tr_b16 v[130:131], v165 offset:4096
	ds_read_b64_tr_b16 v[132:133], v165 offset:6144
	s_add_i32 s17, s17, 16384
	s_cmp_eq_u32 s17, 114688
	s_cselect_b32 s17, 32768, s17
	v_add_u32_e32 v222, s12, v159
	v_add_u32_e32 v223, s12, v160
	v_mfma_f32_32x32x16_bf16 v[98:113], v[134:137], v[142:145], v[98:113]
	ds_read_b64_tr_b16 v[232:233], v216 offset:0
	ds_read_b64_tr_b16 v[234:235], v216 offset:2048
	ds_read_b64_tr_b16 v[134:135], v216 offset:4096
	ds_read_b64_tr_b16 v[136:137], v216 offset:6144
	s_add_i32 s85, s85, 1
	s_cmp_lt_u32 s85, s6
	s_cselect_b32 s8, 0x40000, 0
	s_add_u32 s14, s14, s8
	s_addc_u32 s15, s15, 0
	s_add_u32 s18, s18, s8
	s_addc_u32 s19, s19, 0
	v_mfma_f32_32x32x16_bf16 v[98:113], v[184:187], v[138:141], v[98:113]
	ds_read_b64_tr_b16 v[236:237], v217 offset:0
	ds_read_b64_tr_b16 v[238:239], v217 offset:2048
	ds_read_b64_tr_b16 v[184:185], v217 offset:4096
	ds_read_b64_tr_b16 v[186:187], v217 offset:6144
	s_cbranch_vccz .Lat_norescale_9
	ds_bpermute_b32 v182, v214, v180
	s_waitcnt lgkmcnt(0)
	v_add_f32_e32 v182, v180, v182
	v_min_f32_e32 v182, 0x7f61b1e6, v182
	v_log_f32_e32 v182, v182
	s_nop 0
	v_floor_f32_e32 v182, v182
	v_max_f32_e32 v182, 0, v182
	v_exp_f32_e64 v183, -v182
	v_add_f32_e32 v80, v80, v182
	v_mul_f32_e32 v81, v81, v183
	v_mul_f32_e32 v180, v180, v183
	v_xor_b32_e32 v64, 0x80000000, v80
	v_mov_b32_e32 v65, v64
	v_mov_b32_e32 v66, v64
	v_mov_b32_e32 v67, v64
	v_mov_b32_e32 v68, v64
	v_mov_b32_e32 v69, v64
	v_mov_b32_e32 v70, v64
	v_mov_b32_e32 v71, v64
	v_mov_b32_e32 v72, v64
	v_mov_b32_e32 v73, v64
	v_mov_b32_e32 v74, v64
	v_mov_b32_e32 v75, v64
	v_mov_b32_e32 v76, v64
	v_mov_b32_e32 v77, v64
	v_mov_b32_e32 v78, v64
	v_mov_b32_e32 v79, v64
	v_sub_f32_e32 v82, v82, v182
	v_sub_f32_e32 v83, v83, v182
	v_sub_f32_e32 v84, v84, v182
	v_sub_f32_e32 v85, v85, v182
	v_sub_f32_e32 v86, v86, v182
	v_sub_f32_e32 v87, v87, v182
	v_sub_f32_e32 v88, v88, v182
	v_sub_f32_e32 v89, v89, v182
	v_sub_f32_e32 v90, v90, v182
	v_sub_f32_e32 v91, v91, v182
	v_sub_f32_e32 v92, v92, v182
	v_sub_f32_e32 v93, v93, v182
	v_sub_f32_e32 v94, v94, v182
	v_sub_f32_e32 v95, v95, v182
	v_sub_f32_e32 v96, v96, v182
	v_sub_f32_e32 v97, v97, v182
	v_sub_f32_e32 v98, v98, v182
	v_sub_f32_e32 v99, v99, v182
	v_sub_f32_e32 v100, v100, v182
	v_sub_f32_e32 v101, v101, v182
	v_sub_f32_e32 v102, v102, v182
	v_sub_f32_e32 v103, v103, v182
	v_sub_f32_e32 v104, v104, v182
	v_sub_f32_e32 v105, v105, v182
	v_sub_f32_e32 v106, v106, v182
	v_sub_f32_e32 v107, v107, v182
	v_sub_f32_e32 v108, v108, v182
	v_sub_f32_e32 v109, v109, v182
	v_sub_f32_e32 v110, v110, v182
	v_sub_f32_e32 v111, v111, v182
	v_sub_f32_e32 v112, v112, v182
	v_sub_f32_e32 v113, v113, v182
	v_mul_f32_e32 v0, v0, v183
	v_mul_f32_e32 v1, v1, v183
	v_mul_f32_e32 v2, v2, v183
	v_mul_f32_e32 v3, v3, v183
	v_mul_f32_e32 v4, v4, v183
	v_mul_f32_e32 v5, v5, v183
	v_mul_f32_e32 v6, v6, v183
	v_mul_f32_e32 v7, v7, v183
	v_mul_f32_e32 v8, v8, v183
	v_mul_f32_e32 v9, v9, v183
	v_mul_f32_e32 v10, v10, v183
	v_mul_f32_e32 v11, v11, v183
	v_mul_f32_e32 v12, v12, v183
	v_mul_f32_e32 v13, v13, v183
	v_mul_f32_e32 v14, v14, v183
	v_mul_f32_e32 v15, v15, v183
	v_mul_f32_e32 v16, v16, v183
	v_mul_f32_e32 v17, v17, v183
	v_mul_f32_e32 v18, v18, v183
	v_mul_f32_e32 v19, v19, v183
	v_mul_f32_e32 v20, v20, v183
	v_mul_f32_e32 v21, v21, v183
	v_mul_f32_e32 v22, v22, v183
	v_mul_f32_e32 v23, v23, v183
	v_mul_f32_e32 v24, v24, v183
	v_mul_f32_e32 v25, v25, v183
	v_mul_f32_e32 v26, v26, v183
	v_mul_f32_e32 v27, v27, v183
	v_mul_f32_e32 v28, v28, v183
	v_mul_f32_e32 v29, v29, v183
	v_mul_f32_e32 v30, v30, v183
	v_mul_f32_e32 v31, v31, v183
	v_mul_f32_e32 v32, v32, v183
	v_mul_f32_e32 v33, v33, v183
	v_mul_f32_e32 v34, v34, v183
	v_mul_f32_e32 v35, v35, v183
	v_mul_f32_e32 v36, v36, v183
	v_mul_f32_e32 v37, v37, v183
	v_mul_f32_e32 v38, v38, v183
	v_mul_f32_e32 v39, v39, v183
	v_mul_f32_e32 v40, v40, v183
	v_mul_f32_e32 v41, v41, v183
	v_mul_f32_e32 v42, v42, v183
	v_mul_f32_e32 v43, v43, v183
	v_mul_f32_e32 v44, v44, v183
	v_mul_f32_e32 v45, v45, v183
	v_mul_f32_e32 v46, v46, v183
	v_mul_f32_e32 v47, v47, v183
	v_mul_f32_e32 v48, v48, v183
	v_mul_f32_e32 v49, v49, v183
	v_mul_f32_e32 v50, v50, v183
	v_mul_f32_e32 v51, v51, v183
	v_mul_f32_e32 v52, v52, v183
	v_mul_f32_e32 v53, v53, v183
	v_mul_f32_e32 v54, v54, v183
	v_mul_f32_e32 v55, v55, v183
	v_mul_f32_e32 v56, v56, v183
	v_mul_f32_e32 v57, v57, v183
	v_mul_f32_e32 v58, v58, v183
	v_mul_f32_e32 v59, v59, v183
	v_mul_f32_e32 v60, v60, v183
	v_mul_f32_e32 v61, v61, v183
	v_mul_f32_e32 v62, v62, v183
	v_mul_f32_e32 v63, v63, v183
	v_lshlrev_b32_e32 v181, 16, v114
	v_and_b32_e32 v114, 0xffff0000, v114
	v_mul_f32_e32 v181, v181, v183
	v_mul_f32_e32 v114, v114, v183
	v_cvt_pk_bf16_f32 v114, v181, v114
	v_lshlrev_b32_e32 v181, 16, v115
	v_and_b32_e32 v115, 0xffff0000, v115
	v_mul_f32_e32 v181, v181, v183
	v_mul_f32_e32 v115, v115, v183
	v_cvt_pk_bf16_f32 v115, v181, v115
	v_lshlrev_b32_e32 v181, 16, v116
	v_and_b32_e32 v116, 0xffff0000, v116
	v_mul_f32_e32 v181, v181, v183
	v_mul_f32_e32 v116, v116, v183
	v_cvt_pk_bf16_f32 v116, v181, v116
	v_lshlrev_b32_e32 v181, 16, v117
	v_and_b32_e32 v117, 0xffff0000, v117
	v_mul_f32_e32 v181, v181, v183
	v_mul_f32_e32 v117, v117, v183
	v_cvt_pk_bf16_f32 v117, v181, v117
	v_lshlrev_b32_e32 v181, 16, v118
	v_and_b32_e32 v118, 0xffff0000, v118
	v_mul_f32_e32 v181, v181, v183
	v_mul_f32_e32 v118, v118, v183
	v_cvt_pk_bf16_f32 v118, v181, v118
	v_lshlrev_b32_e32 v181, 16, v119
	v_and_b32_e32 v119, 0xffff0000, v119
	v_mul_f32_e32 v181, v181, v183
	v_mul_f32_e32 v119, v119, v183
	v_cvt_pk_bf16_f32 v119, v181, v119
	v_lshlrev_b32_e32 v181, 16, v120
	v_and_b32_e32 v120, 0xffff0000, v120
	v_mul_f32_e32 v181, v181, v183
	v_mul_f32_e32 v120, v120, v183
	v_cvt_pk_bf16_f32 v120, v181, v120
	v_lshlrev_b32_e32 v181, 16, v121
	v_and_b32_e32 v121, 0xffff0000, v121
	v_mul_f32_e32 v181, v181, v183
	v_mul_f32_e32 v121, v121, v183
	v_cvt_pk_bf16_f32 v121, v181, v121
	v_lshlrev_b32_e32 v181, 16, v122
	v_and_b32_e32 v122, 0xffff0000, v122
	v_mul_f32_e32 v181, v181, v183
	v_mul_f32_e32 v122, v122, v183
	v_cvt_pk_bf16_f32 v122, v181, v122
	v_lshlrev_b32_e32 v181, 16, v123
	v_and_b32_e32 v123, 0xffff0000, v123
	v_mul_f32_e32 v181, v181, v183
	v_mul_f32_e32 v123, v123, v183
	v_cvt_pk_bf16_f32 v123, v181, v123
	v_lshlrev_b32_e32 v181, 16, v124
	v_and_b32_e32 v124, 0xffff0000, v124
	v_mul_f32_e32 v181, v181, v183
	v_mul_f32_e32 v124, v124, v183
	v_cvt_pk_bf16_f32 v124, v181, v124
	v_lshlrev_b32_e32 v181, 16, v125
	v_and_b32_e32 v125, 0xffff0000, v125
	v_mul_f32_e32 v181, v181, v183
	v_mul_f32_e32 v125, v125, v183
	v_cvt_pk_bf16_f32 v125, v181, v125
	v_lshlrev_b32_e32 v181, 16, v126
	v_and_b32_e32 v126, 0xffff0000, v126
	v_mul_f32_e32 v181, v181, v183
	v_mul_f32_e32 v126, v126, v183
	v_cvt_pk_bf16_f32 v126, v181, v126
	v_lshlrev_b32_e32 v181, 16, v127
	v_and_b32_e32 v127, 0xffff0000, v127
	v_mul_f32_e32 v181, v181, v183
	v_mul_f32_e32 v127, v127, v183
	v_cvt_pk_bf16_f32 v127, v181, v127
	v_lshlrev_b32_e32 v181, 16, v128
	v_and_b32_e32 v128, 0xffff0000, v128
	v_mul_f32_e32 v181, v181, v183
	v_mul_f32_e32 v128, v128, v183
	v_cvt_pk_bf16_f32 v128, v181, v128
	v_lshlrev_b32_e32 v181, 16, v129
	v_and_b32_e32 v129, 0xffff0000, v129
	v_mul_f32_e32 v181, v181, v183
	v_mul_f32_e32 v129, v129, v183
	v_cvt_pk_bf16_f32 v129, v181, v129

.Lat_rare_8:
	s_waitcnt lgkmcnt(0)
	s_add_i32 s16, s81, 1
	s_cmp_gt_i32 s5, s16
	s_cbranch_scc1 .Lat_noqk_3
	s_cmp_gt_i32 s5, s81
	s_cbranch_scc1 .Lat_pvonly_6
	s_waitcnt lgkmcnt(14)
	v_mfma_f32_32x32x16_bf16 v[0:15], v[224:227], v[114:117], v[0:15]
	v_exp_f32_e32 v82, v82
	v_exp_f32_e32 v83, v83
	v_mov_b32_e32 v180, 0
	ds_read_b64_tr_b16 v[224:225], v215 offset:8192
	ds_read_b64_tr_b16 v[226:227], v215 offset:10240
	s_waitcnt lgkmcnt(14)
	v_mfma_f32_32x32x16_bf16 v[16:31], v[228:231], v[114:117], v[16:31]
	v_exp_f32_e32 v84, v84
	v_exp_f32_e32 v85, v85
	v_add_f32_e32 v180, v180, v82
	v_add_f32_e32 v180, v180, v83
	ds_read_b64_tr_b16 v[228:229], v165 offset:8192
	ds_read_b64_tr_b16 v[230:231], v165 offset:10240
	s_waitcnt lgkmcnt(14)
	v_mfma_f32_32x32x16_bf16 v[32:47], v[232:235], v[114:117], v[32:47]
	v_exp_f32_e32 v86, v86
	v_exp_f32_e32 v87, v87
	v_add_f32_e32 v180, v180, v84
	v_add_f32_e32 v180, v180, v85
	ds_read_b64_tr_b16 v[232:233], v216 offset:8192
	ds_read_b64_tr_b16 v[234:235], v216 offset:10240
	s_waitcnt lgkmcnt(14)
	v_mfma_f32_32x32x16_bf16 v[48:63], v[236:239], v[114:117], v[48:63]
	v_exp_f32_e32 v88, v88
	v_exp_f32_e32 v89, v89
	v_add_f32_e32 v180, v180, v86
	v_add_f32_e32 v180, v180, v87
	ds_read_b64_tr_b16 v[236:237], v217 offset:8192
	ds_read_b64_tr_b16 v[238:239], v217 offset:10240
	s_waitcnt lgkmcnt(14)
	v_mfma_f32_32x32x16_bf16 v[0:15], v[240:243], v[118:121], v[0:15]
	v_exp_f32_e32 v90, v90
	v_exp_f32_e32 v91, v91
	v_add_f32_e32 v180, v180, v88
	v_add_f32_e32 v180, v180, v89
	v_cvt_pk_bf16_f32 v114, v82, v83
	ds_read_b64_tr_b16 v[240:241], v215 offset:12288
	ds_read_b64_tr_b16 v[242:243], v215 offset:14336
	s_waitcnt lgkmcnt(14)
	v_mfma_f32_32x32x16_bf16 v[16:31], v[130:133], v[118:121], v[16:31]
	v_exp_f32_e32 v92, v92
	v_exp_f32_e32 v93, v93
	v_add_f32_e32 v180, v180, v90
	v_add_f32_e32 v180, v180, v91
	v_cvt_pk_bf16_f32 v115, v84, v85
	ds_read_b64_tr_b16 v[130:131], v165 offset:12288
	ds_read_b64_tr_b16 v[132:133], v165 offset:14336
	s_waitcnt lgkmcnt(14)
	v_mfma_f32_32x32x16_bf16 v[32:47], v[134:137], v[118:121], v[32:47]
	v_exp_f32_e32 v94, v94
	v_exp_f32_e32 v95, v95
	v_add_f32_e32 v180, v180, v92
	v_add_f32_e32 v180, v180, v93
	v_cvt_pk_bf16_f32 v116, v86, v87
	ds_read_b64_tr_b16 v[134:135], v216 offset:12288
	ds_read_b64_tr_b16 v[136:137], v216 offset:14336
	s_waitcnt lgkmcnt(14)
	v_mfma_f32_32x32x16_bf16 v[48:63], v[184:187], v[118:121], v[48:63]
	v_exp_f32_e32 v96, v96
	v_exp_f32_e32 v97, v97
	v_add_f32_e32 v180, v180, v94
	v_add_f32_e32 v180, v180, v95
	v_cvt_pk_bf16_f32 v117, v88, v89
	ds_read_b64_tr_b16 v[184:185], v217 offset:12288
	ds_read_b64_tr_b16 v[186:187], v217 offset:14336
	s_waitcnt lgkmcnt(14)
	v_mfma_f32_32x32x16_bf16 v[0:15], v[224:227], v[122:125], v[0:15]
	v_exp_f32_e32 v98, v98
	v_exp_f32_e32 v99, v99
	v_add_f32_e32 v180, v180, v96
	v_add_f32_e32 v180, v180, v97
	v_cvt_pk_bf16_f32 v118, v90, v91
	s_waitcnt lgkmcnt(12)
	v_mfma_f32_32x32x16_bf16 v[16:31], v[228:231], v[122:125], v[16:31]
	v_exp_f32_e32 v100, v100
	v_exp_f32_e32 v101, v101
	v_add_f32_e32 v180, v180, v98
	v_add_f32_e32 v180, v180, v99
	v_cvt_pk_bf16_f32 v119, v92, v93
	s_waitcnt lgkmcnt(10)
	v_mfma_f32_32x32x16_bf16 v[32:47], v[232:235], v[122:125], v[32:47]
	v_exp_f32_e32 v102, v102
	v_exp_f32_e32 v103, v103
	v_add_f32_e32 v180, v180, v100
	v_add_f32_e32 v180, v180, v101
	v_cvt_pk_bf16_f32 v120, v94, v95
	s_waitcnt lgkmcnt(8)
	v_mfma_f32_32x32x16_bf16 v[48:63], v[236:239], v[122:125], v[48:63]
	v_exp_f32_e32 v104, v104
	v_exp_f32_e32 v105, v105
	v_add_f32_e32 v180, v180, v102
	v_add_f32_e32 v180, v180, v103
	v_cvt_pk_bf16_f32 v121, v96, v97
	ds_read_b128 v[224:227], v188
	ds_read_b128 v[228:231], v189
	ds_read_b128 v[232:235], v222
	ds_read_b128 v[236:239], v223
	s_waitcnt lgkmcnt(10)
	v_mfma_f32_32x32x16_bf16 v[0:15], v[240:243], v[126:129], v[0:15]
	v_exp_f32_e32 v106, v106
	v_exp_f32_e32 v107, v107
	v_add_f32_e32 v180, v180, v104
	v_add_f32_e32 v180, v180, v105
	v_cvt_pk_bf16_f32 v122, v98, v99
	s_waitcnt lgkmcnt(8)
	v_mfma_f32_32x32x16_bf16 v[16:31], v[130:133], v[126:129], v[16:31]
	v_exp_f32_e32 v108, v108
	v_exp_f32_e32 v109, v109
	v_add_f32_e32 v180, v180, v106
	v_add_f32_e32 v180, v180, v107
	v_cvt_pk_bf16_f32 v123, v100, v101
	s_waitcnt lgkmcnt(6)
	v_mfma_f32_32x32x16_bf16 v[32:47], v[134:137], v[126:129], v[32:47]
	v_exp_f32_e32 v110, v110
	v_exp_f32_e32 v111, v111
	v_add_f32_e32 v180, v180, v108
	v_add_f32_e32 v180, v180, v109
	v_cvt_pk_bf16_f32 v124, v102, v103
	s_waitcnt lgkmcnt(4)
	v_mfma_f32_32x32x16_bf16 v[48:63], v[184:187], v[126:129], v[48:63]
	v_exp_f32_e32 v112, v112
	v_exp_f32_e32 v113, v113
	v_add_f32_e32 v180, v180, v110
	v_add_f32_e32 v180, v180, v111
	v_cvt_pk_bf16_f32 v125, v104, v105
	s_nop 0
	v_add_f32_e32 v180, v180, v112
	v_add_f32_e32 v180, v180, v113
	v_cvt_pk_bf16_f32 v126, v106, v107
	v_cvt_pk_bf16_f32 v127, v108, v109
	v_cvt_pk_bf16_f32 v128, v110, v111
	v_cvt_pk_bf16_f32 v129, v112, v113
	v_cmp_ngt_f32_e32 vcc, s23, v180
	s_cbranch_vccz .Lat_norescale_10
	ds_bpermute_b32 v182, v214, v180
	s_waitcnt lgkmcnt(0)
	v_add_f32_e32 v182, v180, v182
	v_min_f32_e32 v182, 0x7f61b1e6, v182
	v_log_f32_e32 v182, v182
	s_nop 0
	v_floor_f32_e32 v182, v182
	v_max_f32_e32 v182, 0, v182
	v_exp_f32_e64 v183, -v182
	v_add_f32_e32 v80, v80, v182
	v_mul_f32_e32 v81, v81, v183
	v_mul_f32_e32 v180, v180, v183
	v_xor_b32_e32 v64, 0x80000000, v80
	v_mov_b32_e32 v65, v64
	v_mov_b32_e32 v66, v64
	v_mov_b32_e32 v67, v64
	v_mov_b32_e32 v68, v64
	v_mov_b32_e32 v69, v64
	v_mov_b32_e32 v70, v64
	v_mov_b32_e32 v71, v64
	v_mov_b32_e32 v72, v64
	v_mov_b32_e32 v73, v64
	v_mov_b32_e32 v74, v64
	v_mov_b32_e32 v75, v64
	v_mov_b32_e32 v76, v64
	v_mov_b32_e32 v77, v64
	v_mov_b32_e32 v78, v64
	v_mov_b32_e32 v79, v64
	v_mul_f32_e32 v82, v82, v183
	v_mul_f32_e32 v83, v83, v183
	v_mul_f32_e32 v84, v84, v183
	v_mul_f32_e32 v85, v85, v183
	v_mul_f32_e32 v86, v86, v183
	v_mul_f32_e32 v87, v87, v183
	v_mul_f32_e32 v88, v88, v183
	v_mul_f32_e32 v89, v89, v183
	v_mul_f32_e32 v90, v90, v183
	v_mul_f32_e32 v91, v91, v183
	v_mul_f32_e32 v92, v92, v183
	v_mul_f32_e32 v93, v93, v183
	v_mul_f32_e32 v94, v94, v183
	v_mul_f32_e32 v95, v95, v183
	v_mul_f32_e32 v96, v96, v183
	v_mul_f32_e32 v97, v97, v183
	v_mul_f32_e32 v98, v98, v183
	v_mul_f32_e32 v99, v99, v183
	v_mul_f32_e32 v100, v100, v183
	v_mul_f32_e32 v101, v101, v183
	v_mul_f32_e32 v102, v102, v183
	v_mul_f32_e32 v103, v103, v183
	v_mul_f32_e32 v104, v104, v183
	v_mul_f32_e32 v105, v105, v183
	v_mul_f32_e32 v106, v106, v183
	v_mul_f32_e32 v107, v107, v183
	v_mul_f32_e32 v108, v108, v183
	v_mul_f32_e32 v109, v109, v183
	v_mul_f32_e32 v110, v110, v183
	v_mul_f32_e32 v111, v111, v183
	v_mul_f32_e32 v112, v112, v183
	v_mul_f32_e32 v113, v113, v183
	v_mul_f32_e32 v0, v0, v183
	v_mul_f32_e32 v1, v1, v183
	v_mul_f32_e32 v2, v2, v183
	v_mul_f32_e32 v3, v3, v183
	v_mul_f32_e32 v4, v4, v183
	v_mul_f32_e32 v5, v5, v183
	v_mul_f32_e32 v6, v6, v183
	v_mul_f32_e32 v7, v7, v183
	v_mul_f32_e32 v8, v8, v183
	v_mul_f32_e32 v9, v9, v183
	v_mul_f32_e32 v10, v10, v183
	v_mul_f32_e32 v11, v11, v183
	v_mul_f32_e32 v12, v12, v183
	v_mul_f32_e32 v13, v13, v183
	v_mul_f32_e32 v14, v14, v183
	v_mul_f32_e32 v15, v15, v183
	v_mul_f32_e32 v16, v16, v183
	v_mul_f32_e32 v17, v17, v183
	v_mul_f32_e32 v18, v18, v183
	v_mul_f32_e32 v19, v19, v183
	v_mul_f32_e32 v20, v20, v183
	v_mul_f32_e32 v21, v21, v183
	v_mul_f32_e32 v22, v22, v183
	v_mul_f32_e32 v23, v23, v183
	v_mul_f32_e32 v24, v24, v183
	v_mul_f32_e32 v25, v25, v183
	v_mul_f32_e32 v26, v26, v183
	v_mul_f32_e32 v27, v27, v183
	v_mul_f32_e32 v28, v28, v183
	v_mul_f32_e32 v29, v29, v183
	v_mul_f32_e32 v30, v30, v183
	v_mul_f32_e32 v31, v31, v183
	v_mul_f32_e32 v32, v32, v183
	v_mul_f32_e32 v33, v33, v183
	v_mul_f32_e32 v34, v34, v183
	v_mul_f32_e32 v35, v35, v183
	v_mul_f32_e32 v36, v36, v183
	v_mul_f32_e32 v37, v37, v183
	v_mul_f32_e32 v38, v38, v183
	v_mul_f32_e32 v39, v39, v183
	v_mul_f32_e32 v40, v40, v183
	v_mul_f32_e32 v41, v41, v183
	v_mul_f32_e32 v42, v42, v183
	v_mul_f32_e32 v43, v43, v183
	v_mul_f32_e32 v44, v44, v183
	v_mul_f32_e32 v45, v45, v183
	v_mul_f32_e32 v46, v46, v183
	v_mul_f32_e32 v47, v47, v183
	v_mul_f32_e32 v48, v48, v183
	v_mul_f32_e32 v49, v49, v183
	v_mul_f32_e32 v50, v50, v183
	v_mul_f32_e32 v51, v51, v183
	v_mul_f32_e32 v52, v52, v183
	v_mul_f32_e32 v53, v53, v183
	v_mul_f32_e32 v54, v54, v183
	v_mul_f32_e32 v55, v55, v183
	v_mul_f32_e32 v56, v56, v183
	v_mul_f32_e32 v57, v57, v183
	v_mul_f32_e32 v58, v58, v183
	v_mul_f32_e32 v59, v59, v183
	v_mul_f32_e32 v60, v60, v183
	v_mul_f32_e32 v61, v61, v183
	v_mul_f32_e32 v62, v62, v183
	v_mul_f32_e32 v63, v63, v183
	v_cvt_pk_bf16_f32 v114, v82, v83
	v_cvt_pk_bf16_f32 v115, v84, v85
	v_cvt_pk_bf16_f32 v116, v86, v87
	v_cvt_pk_bf16_f32 v117, v88, v89
	v_cvt_pk_bf16_f32 v118, v90, v91
	v_cvt_pk_bf16_f32 v119, v92, v93
	v_cvt_pk_bf16_f32 v120, v94, v95
	v_cvt_pk_bf16_f32 v121, v96, v97
	v_cvt_pk_bf16_f32 v122, v98, v99
	v_cvt_pk_bf16_f32 v123, v100, v101
	v_cvt_pk_bf16_f32 v124, v102, v103
	v_cvt_pk_bf16_f32 v125, v104, v105
	v_cvt_pk_bf16_f32 v126, v106, v107
	v_cvt_pk_bf16_f32 v127, v108, v109
	v_cvt_pk_bf16_f32 v128, v110, v111
	v_cvt_pk_bf16_f32 v129, v112, v113

.Lat_noqk_3:
	s_add_i32 m0, s13, s68
	s_nop 0
	global_load_lds_dwordx4 v154, s[14:15]
	s_add_i32 m0, s17, s69
	s_nop 0
	global_load_lds_dwordx4 v155, s[18:19]
	s_add_i32 m0, m0, 0x400
	s_nop 0
	global_load_lds_dwordx4 v156, s[18:19]
	s_add_i32 s13, s13, 8192
	s_cmp_eq_u32 s13, 32768
	s_cselect_b32 s13, 0, s13
	s_add_i32 s17, s17, 16384
	s_cmp_eq_u32 s17, 114688
	s_cselect_b32 s17, 32768, s17
	s_add_i32 s85, s85, 1
	s_cmp_lt_u32 s85, s6
	s_cselect_b32 s8, 0x40000, 0
	s_add_u32 s14, s14, s8
	s_addc_u32 s15, s15, 0
	s_add_u32 s18, s18, s8
	s_addc_u32 s19, s19, 0
	s_add_i32 s5, s5, 1
	s_add_i32 s12, s12, 8192
	s_cmp_eq_u32 s12, 32768
	s_cselect_b32 s12, 0, s12
	s_add_i32 s84, s84, 16384
	s_cmp_eq_u32 s84, 114688
	s_cselect_b32 s84, 32768, s84
	v_add_u32_e32 v188, s12, v157
	v_add_u32_e32 v189, s12, v158
	v_add_u32_e32 v222, s12, v159
	v_add_u32_e32 v223, s12, v160
	s_add_i32 s16, s81, 1
	s_cmp_gt_i32 s5, s16
	s_cbranch_scc1 .Lat_novpre_5
	v_add_u32_e32 v215, s84, v161
	v_add_u32_e32 v165, s84, v162
	v_add_u32_e32 v216, s84, v163
	v_add_u32_e32 v217, s84, v164
	ds_read_b64_tr_b16 v[224:225], v215 offset:0
	ds_read_b64_tr_b16 v[226:227], v215 offset:2048
	ds_read_b64_tr_b16 v[228:229], v165 offset:0
	ds_read_b64_tr_b16 v[230:231], v165 offset:2048
	ds_read_b64_tr_b16 v[232:233], v216 offset:0
	ds_read_b64_tr_b16 v[234:235], v216 offset:2048
	ds_read_b64_tr_b16 v[236:237], v217 offset:0
	ds_read_b64_tr_b16 v[238:239], v217 offset:2048
	ds_read_b64_tr_b16 v[240:241], v215 offset:4096
	ds_read_b64_tr_b16 v[242:243], v215 offset:6144
	ds_read_b64_tr_b16 v[130:131], v165 offset:4096
	ds_read_b64_tr_b16 v[132:133], v165 offset:6144
	ds_read_b64_tr_b16 v[134:135], v216 offset:4096
	ds_read_b64_tr_b16 v[136:137], v216 offset:6144
	ds_read_b64_tr_b16 v[184:185], v217 offset:4096
	ds_read_b64_tr_b16 v[186:187], v217 offset:6144
	s_waitcnt vmcnt(3) lgkmcnt(15)
	s_branch .Lat_bottom_4
